# grid-barrier poll loops sleep 20 instead of 4 between polls (less polling traffic while tail workgroups finish)
# speedup vs baseline: 1.0196x; 1.0095x over previous
.LBB0_37:
	s_sleep 20
	global_load_dword v1, v0, s[8:9] sc1
	s_waitcnt vmcnt(0)
	v_cmp_gt_u32_e32 vcc, s2, v1
	s_cbranch_vccnz .LBB0_37

.LBB0_113:
	s_sleep 20
	global_load_dword v1, v0, s[10:11] sc1
	s_waitcnt vmcnt(0)
	v_cmp_gt_u32_e32 vcc, s2, v1
	s_cbranch_vccnz .LBB0_113

.LBB0_151:
	s_sleep 20
	global_load_dword v1, v0, s[6:7] sc1
	s_waitcnt vmcnt(0)
	v_cmp_gt_u32_e32 vcc, s2, v1
	s_cbranch_vccnz .LBB0_151

.LBB0_613:
	s_sleep 20
	global_load_dword v1, v0, s[10:11] sc1
	s_waitcnt vmcnt(0)
	v_cmp_gt_u32_e32 vcc, s3, v1
	s_cbranch_vccnz .LBB0_613

.Lfb_poll:
	global_load_dword v1, v0, s[10:11] offset:512 sc1
	s_waitcnt vmcnt(0)
	v_cmp_gt_u32_e32 vcc, 8, v1
	s_cbranch_vccz .Lfb_done
	s_sleep 20
	s_branch .Lfb_poll

.LBB0_702:
	s_sleep 20
	global_load_dword v1, v0, s[10:11] sc1
	s_waitcnt vmcnt(0)
	v_cmp_gt_u32_e32 vcc, s7, v1
	s_cbranch_vccnz .LBB0_702
